# decode attention P*V with 16-byte loads / copy stores (4 keys per instruction, key groups added with permlane swaps) instead of 4-byte ones
# speedup vs baseline: 1.0063x; 1.0063x over previous
.LBB0_2684:
	s_or_b64 exec, exec, s[22:23]
	s_and_b32 s19, s30, 3
	s_lshl_b32 s19, s19, 8
	s_lshl_b64 s[20:21], s[20:21], 17
	s_or_b32 s22, s20, s19
	s_mov_b32 s23, s21
	v_lshl_add_u64 v[12:13], v[8:9], 0, s[22:23]
	v_lshl_add_u64 v[14:15], v[10:11], 0, s[22:23]
	v_mov_b32_e32 v32, 0
	s_mov_b64 s[22:23], 0
	v_mov_b32_e32 v33, v30
	v_mov_b32_e32 v34, v4
	s_waitcnt lgkmcnt(0)
	s_barrier
	s_mov_b32 s24, 0x1000
	s_mov_b32 s25, 0
	v_and_b32_e32 v252, 63, v174
	v_lshrrev_b32_e32 v213, 4, v252
	v_and_b32_e32 v253, 15, v252
	v_mul_u32_u24_e32 v210, 0x3c0, v213
	v_mad_u32_u24 v210, v253, 12, v210
	v_mov_b32_e32 v211, 0
	v_lshl_add_u64 v[206:207], v[12:13], 0, v[210:211]
	v_lshl_add_u64 v[208:209], v[14:15], 0, v[210:211]
	v_lshl_add_u32 v212, v213, 2, v33
	v_lshrrev_b32_e32 v214, 6, v174
	v_lshlrev_b32_e32 v214, 8, v214
	v_add_u32_e32 v214, 0x2000, v214
	v_lshl_add_u32 v215, v252, 2, v214
	v_lshl_add_u32 v214, v253, 4, v214
	v_mov_b32_e32 v232, 0
	v_mov_b32_e32 v233, 0
	v_mov_b32_e32 v234, 0
	v_mov_b32_e32 v235, 0
	s_cmp_eq_u64 s[14:15], 0
	s_cbranch_scc1 .Ladec_nost
	ds_read_b32 v236, v212 offset:0
	ds_read_b32 v237, v212 offset:16
	ds_read_b32 v238, v212 offset:32
	ds_read_b32 v239, v212 offset:48
	ds_read_b32 v240, v212 offset:64
	ds_read_b32 v241, v212 offset:80
	ds_read_b32 v242, v212 offset:96
	ds_read_b32 v243, v212 offset:112
	ds_read_b32 v244, v212 offset:128
	ds_read_b32 v245, v212 offset:144
	ds_read_b32 v246, v212 offset:160
	ds_read_b32 v247, v212 offset:176
	ds_read_b32 v248, v212 offset:192
	ds_read_b32 v249, v212 offset:208
	ds_read_b32 v250, v212 offset:224
	ds_read_b32 v251, v212 offset:240
	global_load_dwordx4 v[216:219], v[206:207], off
	v_lshl_add_u64 v[206:207], v[206:207], 0, s[24:25]
	global_load_dwordx4 v[220:223], v[206:207], off
	v_lshl_add_u64 v[206:207], v[206:207], 0, s[24:25]
	global_load_dwordx4 v[224:227], v[206:207], off
	v_lshl_add_u64 v[206:207], v[206:207], 0, s[24:25]
	s_waitcnt vmcnt(2) lgkmcnt(15)
	v_fmac_f32_e32 v232, v236, v216
	v_fmac_f32_e32 v233, v236, v217
	v_fmac_f32_e32 v234, v236, v218
	v_fmac_f32_e32 v235, v236, v219
	v_add_u32_e32 v252, v34, v213
	v_cmp_lt_i32_e32 vcc, 0, v252
	s_and_saveexec_b64 s[26:27], vcc
	global_store_dwordx4 v[208:209], v[216:219], off offset:-2048
	s_or_b64 exec, exec, s[26:27]
	v_lshl_add_u64 v[208:209], v[208:209], 0, s[24:25]
	global_load_dwordx4 v[228:231], v[206:207], off
	v_lshl_add_u64 v[206:207], v[206:207], 0, s[24:25]
	s_waitcnt vmcnt(3) lgkmcnt(14)
	v_fmac_f32_e32 v232, v237, v220
	v_fmac_f32_e32 v233, v237, v221
	v_fmac_f32_e32 v234, v237, v222
	v_fmac_f32_e32 v235, v237, v223
	global_store_dwordx4 v[208:209], v[220:223], off offset:-2048
	v_lshl_add_u64 v[208:209], v[208:209], 0, s[24:25]
	global_load_dwordx4 v[216:219], v[206:207], off
	v_lshl_add_u64 v[206:207], v[206:207], 0, s[24:25]
	s_waitcnt vmcnt(4) lgkmcnt(13)
	v_fmac_f32_e32 v232, v238, v224
	v_fmac_f32_e32 v233, v238, v225
	v_fmac_f32_e32 v234, v238, v226
	v_fmac_f32_e32 v235, v238, v227
	global_store_dwordx4 v[208:209], v[224:227], off offset:-2048
	v_lshl_add_u64 v[208:209], v[208:209], 0, s[24:25]
	global_load_dwordx4 v[220:223], v[206:207], off
	v_lshl_add_u64 v[206:207], v[206:207], 0, s[24:25]
	s_waitcnt vmcnt(4) lgkmcnt(12)
	v_fmac_f32_e32 v232, v239, v228
	v_fmac_f32_e32 v233, v239, v229
	v_fmac_f32_e32 v234, v239, v230
	v_fmac_f32_e32 v235, v239, v231
	global_store_dwordx4 v[208:209], v[228:231], off offset:-2048
	v_lshl_add_u64 v[208:209], v[208:209], 0, s[24:25]
	global_load_dwordx4 v[224:227], v[206:207], off
	v_lshl_add_u64 v[206:207], v[206:207], 0, s[24:25]
	s_waitcnt vmcnt(4) lgkmcnt(11)
	v_fmac_f32_e32 v232, v240, v216
	v_fmac_f32_e32 v233, v240, v217
	v_fmac_f32_e32 v234, v240, v218
	v_fmac_f32_e32 v235, v240, v219
	global_store_dwordx4 v[208:209], v[216:219], off offset:-2048
	v_lshl_add_u64 v[208:209], v[208:209], 0, s[24:25]
	global_load_dwordx4 v[228:231], v[206:207], off
	v_lshl_add_u64 v[206:207], v[206:207], 0, s[24:25]
	s_waitcnt vmcnt(4) lgkmcnt(10)
	v_fmac_f32_e32 v232, v241, v220
	v_fmac_f32_e32 v233, v241, v221
	v_fmac_f32_e32 v234, v241, v222
	v_fmac_f32_e32 v235, v241, v223
	global_store_dwordx4 v[208:209], v[220:223], off offset:-2048
	v_lshl_add_u64 v[208:209], v[208:209], 0, s[24:25]
	global_load_dwordx4 v[216:219], v[206:207], off
	v_lshl_add_u64 v[206:207], v[206:207], 0, s[24:25]
	s_waitcnt vmcnt(4) lgkmcnt(9)
	v_fmac_f32_e32 v232, v242, v224
	v_fmac_f32_e32 v233, v242, v225
	v_fmac_f32_e32 v234, v242, v226
	v_fmac_f32_e32 v235, v242, v227
	global_store_dwordx4 v[208:209], v[224:227], off offset:-2048
	v_lshl_add_u64 v[208:209], v[208:209], 0, s[24:25]
	global_load_dwordx4 v[220:223], v[206:207], off
	v_lshl_add_u64 v[206:207], v[206:207], 0, s[24:25]
	s_waitcnt vmcnt(4) lgkmcnt(8)
	v_fmac_f32_e32 v232, v243, v228
	v_fmac_f32_e32 v233, v243, v229
	v_fmac_f32_e32 v234, v243, v230
	v_fmac_f32_e32 v235, v243, v231
	global_store_dwordx4 v[208:209], v[228:231], off offset:-2048
	v_lshl_add_u64 v[208:209], v[208:209], 0, s[24:25]
	global_load_dwordx4 v[224:227], v[206:207], off
	v_lshl_add_u64 v[206:207], v[206:207], 0, s[24:25]
	s_waitcnt vmcnt(4) lgkmcnt(7)
	v_fmac_f32_e32 v232, v244, v216
	v_fmac_f32_e32 v233, v244, v217
	v_fmac_f32_e32 v234, v244, v218
	v_fmac_f32_e32 v235, v244, v219
	global_store_dwordx4 v[208:209], v[216:219], off offset:-2048
	v_lshl_add_u64 v[208:209], v[208:209], 0, s[24:25]
	global_load_dwordx4 v[228:231], v[206:207], off
	v_lshl_add_u64 v[206:207], v[206:207], 0, s[24:25]
	s_waitcnt vmcnt(4) lgkmcnt(6)
	v_fmac_f32_e32 v232, v245, v220
	v_fmac_f32_e32 v233, v245, v221
	v_fmac_f32_e32 v234, v245, v222
	v_fmac_f32_e32 v235, v245, v223
	global_store_dwordx4 v[208:209], v[220:223], off offset:-2048
	v_lshl_add_u64 v[208:209], v[208:209], 0, s[24:25]
	global_load_dwordx4 v[216:219], v[206:207], off
	v_lshl_add_u64 v[206:207], v[206:207], 0, s[24:25]
	s_waitcnt vmcnt(4) lgkmcnt(5)
	v_fmac_f32_e32 v232, v246, v224
	v_fmac_f32_e32 v233, v246, v225
	v_fmac_f32_e32 v234, v246, v226
	v_fmac_f32_e32 v235, v246, v227
	global_store_dwordx4 v[208:209], v[224:227], off offset:-2048
	v_lshl_add_u64 v[208:209], v[208:209], 0, s[24:25]
	global_load_dwordx4 v[220:223], v[206:207], off
	v_lshl_add_u64 v[206:207], v[206:207], 0, s[24:25]
	s_waitcnt vmcnt(4) lgkmcnt(4)
	v_fmac_f32_e32 v232, v247, v228
	v_fmac_f32_e32 v233, v247, v229
	v_fmac_f32_e32 v234, v247, v230
	v_fmac_f32_e32 v235, v247, v231
	global_store_dwordx4 v[208:209], v[228:231], off offset:-2048
	v_lshl_add_u64 v[208:209], v[208:209], 0, s[24:25]
	global_load_dwordx4 v[224:227], v[206:207], off
	v_lshl_add_u64 v[206:207], v[206:207], 0, s[24:25]
	s_waitcnt vmcnt(4) lgkmcnt(3)
	v_fmac_f32_e32 v232, v248, v216
	v_fmac_f32_e32 v233, v248, v217
	v_fmac_f32_e32 v234, v248, v218
	v_fmac_f32_e32 v235, v248, v219
	global_store_dwordx4 v[208:209], v[216:219], off offset:-2048
	v_lshl_add_u64 v[208:209], v[208:209], 0, s[24:25]
	global_load_dwordx4 v[228:231], v[206:207], off
	v_lshl_add_u64 v[206:207], v[206:207], 0, s[24:25]
	s_waitcnt vmcnt(4) lgkmcnt(2)
	v_fmac_f32_e32 v232, v249, v220
	v_fmac_f32_e32 v233, v249, v221
	v_fmac_f32_e32 v234, v249, v222
	v_fmac_f32_e32 v235, v249, v223
	global_store_dwordx4 v[208:209], v[220:223], off offset:-2048
	v_lshl_add_u64 v[208:209], v[208:209], 0, s[24:25]
	s_waitcnt vmcnt(3) lgkmcnt(1)
	v_fmac_f32_e32 v232, v250, v224
	v_fmac_f32_e32 v233, v250, v225
	v_fmac_f32_e32 v234, v250, v226
	v_fmac_f32_e32 v235, v250, v227
	global_store_dwordx4 v[208:209], v[224:227], off offset:-2048
	v_lshl_add_u64 v[208:209], v[208:209], 0, s[24:25]
	s_waitcnt vmcnt(2) lgkmcnt(0)
	v_fmac_f32_e32 v232, v251, v228
	v_fmac_f32_e32 v233, v251, v229
	v_fmac_f32_e32 v234, v251, v230
	v_fmac_f32_e32 v235, v251, v231
	global_store_dwordx4 v[208:209], v[228:231], off offset:-2048
	v_lshl_add_u64 v[208:209], v[208:209], 0, s[24:25]
	s_branch .Ladec_red
.Ladec_nost:
	ds_read_b32 v236, v212 offset:0
	ds_read_b32 v237, v212 offset:16
	ds_read_b32 v238, v212 offset:32
	ds_read_b32 v239, v212 offset:48
	ds_read_b32 v240, v212 offset:64
	ds_read_b32 v241, v212 offset:80
	ds_read_b32 v242, v212 offset:96
	ds_read_b32 v243, v212 offset:112
	ds_read_b32 v244, v212 offset:128
	ds_read_b32 v245, v212 offset:144
	ds_read_b32 v246, v212 offset:160
	ds_read_b32 v247, v212 offset:176
	ds_read_b32 v248, v212 offset:192
	ds_read_b32 v249, v212 offset:208
	ds_read_b32 v250, v212 offset:224
	ds_read_b32 v251, v212 offset:240
	global_load_dwordx4 v[216:219], v[206:207], off
	v_lshl_add_u64 v[206:207], v[206:207], 0, s[24:25]
	global_load_dwordx4 v[220:223], v[206:207], off
	v_lshl_add_u64 v[206:207], v[206:207], 0, s[24:25]
	global_load_dwordx4 v[224:227], v[206:207], off
	v_lshl_add_u64 v[206:207], v[206:207], 0, s[24:25]
	s_waitcnt vmcnt(2) lgkmcnt(15)
	v_fmac_f32_e32 v232, v236, v216
	v_fmac_f32_e32 v233, v236, v217
	v_fmac_f32_e32 v234, v236, v218
	v_fmac_f32_e32 v235, v236, v219
	global_load_dwordx4 v[228:231], v[206:207], off
	v_lshl_add_u64 v[206:207], v[206:207], 0, s[24:25]
	s_waitcnt vmcnt(2) lgkmcnt(14)
	v_fmac_f32_e32 v232, v237, v220
	v_fmac_f32_e32 v233, v237, v221
	v_fmac_f32_e32 v234, v237, v222
	v_fmac_f32_e32 v235, v237, v223
	global_load_dwordx4 v[216:219], v[206:207], off
	v_lshl_add_u64 v[206:207], v[206:207], 0, s[24:25]
	s_waitcnt vmcnt(2) lgkmcnt(13)
	v_fmac_f32_e32 v232, v238, v224
	v_fmac_f32_e32 v233, v238, v225
	v_fmac_f32_e32 v234, v238, v226
	v_fmac_f32_e32 v235, v238, v227
	global_load_dwordx4 v[220:223], v[206:207], off
	v_lshl_add_u64 v[206:207], v[206:207], 0, s[24:25]
	s_waitcnt vmcnt(2) lgkmcnt(12)
	v_fmac_f32_e32 v232, v239, v228
	v_fmac_f32_e32 v233, v239, v229
	v_fmac_f32_e32 v234, v239, v230
	v_fmac_f32_e32 v235, v239, v231
	global_load_dwordx4 v[224:227], v[206:207], off
	v_lshl_add_u64 v[206:207], v[206:207], 0, s[24:25]
	s_waitcnt vmcnt(2) lgkmcnt(11)
	v_fmac_f32_e32 v232, v240, v216
	v_fmac_f32_e32 v233, v240, v217
	v_fmac_f32_e32 v234, v240, v218
	v_fmac_f32_e32 v235, v240, v219
	global_load_dwordx4 v[228:231], v[206:207], off
	v_lshl_add_u64 v[206:207], v[206:207], 0, s[24:25]
	s_waitcnt vmcnt(2) lgkmcnt(10)
	v_fmac_f32_e32 v232, v241, v220
	v_fmac_f32_e32 v233, v241, v221
	v_fmac_f32_e32 v234, v241, v222
	v_fmac_f32_e32 v235, v241, v223
	global_load_dwordx4 v[216:219], v[206:207], off
	v_lshl_add_u64 v[206:207], v[206:207], 0, s[24:25]
	s_waitcnt vmcnt(2) lgkmcnt(9)
	v_fmac_f32_e32 v232, v242, v224
	v_fmac_f32_e32 v233, v242, v225
	v_fmac_f32_e32 v234, v242, v226
	v_fmac_f32_e32 v235, v242, v227
	global_load_dwordx4 v[220:223], v[206:207], off
	v_lshl_add_u64 v[206:207], v[206:207], 0, s[24:25]
	s_waitcnt vmcnt(2) lgkmcnt(8)
	v_fmac_f32_e32 v232, v243, v228
	v_fmac_f32_e32 v233, v243, v229
	v_fmac_f32_e32 v234, v243, v230
	v_fmac_f32_e32 v235, v243, v231
	global_load_dwordx4 v[224:227], v[206:207], off
	v_lshl_add_u64 v[206:207], v[206:207], 0, s[24:25]
	s_waitcnt vmcnt(2) lgkmcnt(7)
	v_fmac_f32_e32 v232, v244, v216
	v_fmac_f32_e32 v233, v244, v217
	v_fmac_f32_e32 v234, v244, v218
	v_fmac_f32_e32 v235, v244, v219
	global_load_dwordx4 v[228:231], v[206:207], off
	v_lshl_add_u64 v[206:207], v[206:207], 0, s[24:25]
	s_waitcnt vmcnt(2) lgkmcnt(6)
	v_fmac_f32_e32 v232, v245, v220
	v_fmac_f32_e32 v233, v245, v221
	v_fmac_f32_e32 v234, v245, v222
	v_fmac_f32_e32 v235, v245, v223
	global_load_dwordx4 v[216:219], v[206:207], off
	v_lshl_add_u64 v[206:207], v[206:207], 0, s[24:25]
	s_waitcnt vmcnt(2) lgkmcnt(5)
	v_fmac_f32_e32 v232, v246, v224
	v_fmac_f32_e32 v233, v246, v225
	v_fmac_f32_e32 v234, v246, v226
	v_fmac_f32_e32 v235, v246, v227
	global_load_dwordx4 v[220:223], v[206:207], off
	v_lshl_add_u64 v[206:207], v[206:207], 0, s[24:25]
	s_waitcnt vmcnt(2) lgkmcnt(4)
	v_fmac_f32_e32 v232, v247, v228
	v_fmac_f32_e32 v233, v247, v229
	v_fmac_f32_e32 v234, v247, v230
	v_fmac_f32_e32 v235, v247, v231
	global_load_dwordx4 v[224:227], v[206:207], off
	v_lshl_add_u64 v[206:207], v[206:207], 0, s[24:25]
	s_waitcnt vmcnt(2) lgkmcnt(3)
	v_fmac_f32_e32 v232, v248, v216
	v_fmac_f32_e32 v233, v248, v217
	v_fmac_f32_e32 v234, v248, v218
	v_fmac_f32_e32 v235, v248, v219
	global_load_dwordx4 v[228:231], v[206:207], off
	v_lshl_add_u64 v[206:207], v[206:207], 0, s[24:25]
	s_waitcnt vmcnt(2) lgkmcnt(2)
	v_fmac_f32_e32 v232, v249, v220
	v_fmac_f32_e32 v233, v249, v221
	v_fmac_f32_e32 v234, v249, v222
	v_fmac_f32_e32 v235, v249, v223
	s_waitcnt vmcnt(1) lgkmcnt(1)
	v_fmac_f32_e32 v232, v250, v224
	v_fmac_f32_e32 v233, v250, v225
	v_fmac_f32_e32 v234, v250, v226
	v_fmac_f32_e32 v235, v250, v227
	s_waitcnt vmcnt(0) lgkmcnt(0)
	v_fmac_f32_e32 v232, v251, v228
	v_fmac_f32_e32 v233, v251, v229
	v_fmac_f32_e32 v234, v251, v230
	v_fmac_f32_e32 v235, v251, v231
.Ladec_red:
	v_mov_b32_e32 v252, v232
	s_nop 1
	v_permlane32_swap_b32_e32 v252, v232
	v_add_f32_e32 v232, v232, v252
	v_mov_b32_e32 v254, v232
	s_nop 1
	v_permlane16_swap_b32_e32 v254, v232
	v_add_f32_e32 v232, v232, v254
	v_mov_b32_e32 v253, v233
	s_nop 1
	v_permlane32_swap_b32_e32 v253, v233
	v_add_f32_e32 v233, v233, v253
	v_mov_b32_e32 v255, v233
	s_nop 1
	v_permlane16_swap_b32_e32 v255, v233
	v_add_f32_e32 v233, v233, v255
	v_mov_b32_e32 v252, v234
	s_nop 1
	v_permlane32_swap_b32_e32 v252, v234
	v_add_f32_e32 v234, v234, v252
	v_mov_b32_e32 v254, v234
	s_nop 1
	v_permlane16_swap_b32_e32 v254, v234
	v_add_f32_e32 v234, v234, v254
	v_mov_b32_e32 v253, v235
	s_nop 1
	v_permlane32_swap_b32_e32 v253, v235
	v_add_f32_e32 v235, v235, v253
	v_mov_b32_e32 v255, v235
	s_nop 1
	v_permlane16_swap_b32_e32 v255, v235
	v_add_f32_e32 v235, v235, v255
	s_mov_b64 s[26:27], exec
	s_mov_b64 exec, 0xffff
	ds_write_b128 v214, v[232:235]
	s_mov_b64 exec, s[26:27]
	s_waitcnt lgkmcnt(0)
	ds_read_b32 v32, v215
	s_waitcnt lgkmcnt(0)
